# XCD-local barrier: waiting WGs poll the arrival counter directly, last arriver skips the release add
# baseline (speedup 1.0000x reference)
; __device__ __forceinline__ unsigned xb_ld(unsigned* p)              { return __hip_atomic_load(p, __ATOMIC_RELAXED, __HIP_MEMORY_SCOPE_AGENT); }
; __device__ __forceinline__ unsigned xb_add(unsigned* p, unsigned v) { return __hip_atomic_fetch_add(p, v, __ATOMIC_RELAXED, __HIP_MEMORY_SCOPE_AGENT); }
; #define XB_SPIN(cond, bar) do { unsigned _sp = 0; while (cond) { __builtin_amdgcn_s_sleep(1); \
;     if ((++_sp & 255u) == 0u) { if (xb_ld(&(bar)[XB_TMO])) break; if (_sp > XB_SPIN_CAP) { atomicAdd(&(bar)[XB_TMO], 1u); break; } } } } while (0)
; __device__ __forceinline__ void xcd_barrier(const XcdBarrier& b) {
;     ...
;         const unsigned old = xb_add(&bar[XB_XSUB(b.x)], 1u);
;         const unsigned gen = old / nloc;
;         if (old + 1u == (gen + 1u) * nloc) {
;             __builtin_amdgcn_fence(__ATOMIC_RELEASE, "agent");
;             asm volatile("s_waitcnt vmcnt(0)" ::: "memory");
;             const unsigned og = xb_add(&bar[XB_TOP], 1u);
;             const unsigned tg = og / nx;
;             if (og + 1u == (tg + 1u) * nx) xb_add(&bar[XB_TOPGEN], 1u);
;             else XB_SPIN(xb_ld(&bar[XB_TOPGEN]) == tg, bar);
;             __builtin_amdgcn_fence(__ATOMIC_ACQUIRE, "agent");
;             xb_add(&bar[XB_XGEN(b.x)], 1u);
;             asm volatile("s_waitcnt vmcnt(0)" ::: "memory");
;         } else {
;             XB_SPIN(xb_ld(&bar[XB_XGEN(b.x)]) == gen, bar);
;             __builtin_amdgcn_fence(__ATOMIC_ACQUIRE, "agent");
;             asm volatile("s_waitcnt vmcnt(0)" ::: "memory");
;         }
.LBB0_464:
	s_or_b64 exec, exec, s[8:9]
	v_cvt_f32_u32_e32 v4, v2
	s_waitcnt vmcnt(0)
	v_readfirstlane_b32 s2, v3
	v_sub_u32_e32 v3, 0, v2
	v_rcp_iflag_f32_e32 v4, v4
	v_add_u32_e32 v5, s2, v1
	v_mul_f32_e32 v4, 0x4f7ffffe, v4
	v_cvt_u32_f32_e32 v4, v4
	v_mul_lo_u32 v1, v3, v4
	v_mul_hi_u32 v1, v4, v1
	v_add_u32_e32 v1, v4, v1
	v_mul_hi_u32 v1, v5, v1
	v_mul_lo_u32 v3, v1, v2
	v_sub_u32_e32 v3, v5, v3
	v_add_u32_e32 v4, 1, v1
	v_cmp_ge_u32_e32 vcc, v3, v2
	s_nop 1
	v_cndmask_b32_e32 v1, v1, v4, vcc
	v_sub_u32_e32 v4, v3, v2
	v_cndmask_b32_e32 v3, v3, v4, vcc
	v_add_u32_e32 v4, 1, v1
	v_cmp_ge_u32_e32 vcc, v3, v2
	v_add_u32_e32 v3, 1, v5
	s_nop 0
	v_cndmask_b32_e32 v1, v1, v4, vcc
	v_mul_lo_u32 v4, v2, v1
	v_add_u32_e32 v2, v4, v2
	v_cmp_ne_u32_e32 vcc, v3, v2
	s_and_saveexec_b64 s[6:7], vcc
	s_xor_b64 s[6:7], exec, s[6:7]
	s_cbranch_execz .LBB0_478
	s_waitcnt lgkmcnt(0)
	s_cmp_lg_u32 s98, 0
	s_cbranch_scc1 .Llp2_std
	v_mov_b32_e32 v0, 0x1000
	s_mov_b32 s14, 0
.Llp2_spin:
	global_load_dword v4, v0, s[4:5] offset:1024 sc1
	s_waitcnt vmcnt(0)
	v_cmp_lt_u32_e32 vcc, v4, v2
	s_cbranch_vccz .Llp2_out
	s_sleep 1
	s_add_i32 s14, s14, 1
	s_cmp_lt_u32 s14, 0x100000
	s_cbranch_scc1 .Llp2_spin
.Llp2_out:
	s_mov_b64 s[8:9], exec
	s_branch .LBB0_477
.Llp2_std:
	v_mov_b32_e32 v0, 0x2000
	global_load_dword v0, v0, s[4:5] offset:1024 sc1
	s_add_u32 s12, s4, 0x2400
	s_addc_u32 s13, s5, 0
	s_waitcnt vmcnt(0)
	v_cmp_eq_u32_e32 vcc, v0, v1
	s_and_saveexec_b64 s[8:9], vcc
	s_cbranch_execz .LBB0_477
	s_add_u32 s10, s50, 0x1180200
	s_addc_u32 s11, s51, 0
	s_mov_b32 s2, 1
	s_mov_b64 s[14:15], 0
	v_mov_b32_e32 v0, 0
	s_branch .LBB0_468

; __device__ __forceinline__ unsigned xb_add(unsigned* p, unsigned v) { return __hip_atomic_fetch_add(p, v, __ATOMIC_RELAXED, __HIP_MEMORY_SCOPE_AGENT); }
; __device__ __forceinline__ void xcd_barrier(const XcdBarrier& b) {
;     ...
;             __builtin_amdgcn_fence(__ATOMIC_ACQUIRE, "agent");
;             xb_add(&bar[XB_XGEN(b.x)], 1u);
;             asm volatile("s_waitcnt vmcnt(0)" ::: "memory");
.LBB0_495:
	s_or_b64 exec, exec, s[8:9]
	s_mov_b64 s[8:9], exec
	v_mbcnt_lo_u32_b32 v0, s8, 0
	v_mbcnt_hi_u32_b32 v0, s9, v0
	v_cmp_eq_u32_e32 vcc, 0, v0
	s_waitcnt vmcnt(0)
	buffer_inv sc1
	s_cmp_eq_u32 s98, 0
	s_cbranch_scc1 .Lnx2
	s_and_saveexec_b64 s[10:11], vcc
	s_cbranch_execz .LBB0_497
	s_bcnt1_i32_b64 s2, s[8:9]
	v_mov_b32_e32 v0, 0x2000
	v_mov_b32_e32 v1, s2
	global_atomic_add v0, v1, s[4:5] offset:1024
.LBB0_497:
	s_or_b64 exec, exec, s[10:11]
.Lnx2:
	s_waitcnt vmcnt(0)
.LBB0_498:
	s_or_b64 exec, exec, s[6:7]

; __device__ __forceinline__ unsigned xb_ld(unsigned* p)              { return __hip_atomic_load(p, __ATOMIC_RELAXED, __HIP_MEMORY_SCOPE_AGENT); }
; __device__ __forceinline__ unsigned xb_add(unsigned* p, unsigned v) { return __hip_atomic_fetch_add(p, v, __ATOMIC_RELAXED, __HIP_MEMORY_SCOPE_AGENT); }
; #define XB_SPIN(cond, bar) do { unsigned _sp = 0; while (cond) { __builtin_amdgcn_s_sleep(1); \
;     if ((++_sp & 255u) == 0u) { if (xb_ld(&(bar)[XB_TMO])) break; if (_sp > XB_SPIN_CAP) { atomicAdd(&(bar)[XB_TMO], 1u); break; } } } } while (0)
; __device__ __forceinline__ void xcd_barrier(const XcdBarrier& b) {
;     ...
;         const unsigned old = xb_add(&bar[XB_XSUB(b.x)], 1u);
;         const unsigned gen = old / nloc;
;         if (old + 1u == (gen + 1u) * nloc) {
;             __builtin_amdgcn_fence(__ATOMIC_RELEASE, "agent");
;             asm volatile("s_waitcnt vmcnt(0)" ::: "memory");
;             const unsigned og = xb_add(&bar[XB_TOP], 1u);
;             const unsigned tg = og / nx;
;             if (og + 1u == (tg + 1u) * nx) xb_add(&bar[XB_TOPGEN], 1u);
;             else XB_SPIN(xb_ld(&bar[XB_TOPGEN]) == tg, bar);
;             __builtin_amdgcn_fence(__ATOMIC_ACQUIRE, "agent");
;             xb_add(&bar[XB_XGEN(b.x)], 1u);
;             asm volatile("s_waitcnt vmcnt(0)" ::: "memory");
;         } else {
;             XB_SPIN(xb_ld(&bar[XB_XGEN(b.x)]) == gen, bar);
;             __builtin_amdgcn_fence(__ATOMIC_ACQUIRE, "agent");
;             asm volatile("s_waitcnt vmcnt(0)" ::: "memory");
;         }
.LBB0_700:
	s_or_b64 exec, exec, s[10:11]
	v_cvt_f32_u32_e32 v4, v2
	s_waitcnt vmcnt(0)
	v_readfirstlane_b32 s0, v3
	v_sub_u32_e32 v3, 0, v2
	v_rcp_iflag_f32_e32 v4, v4
	v_add_u32_e32 v5, s0, v1
	v_mul_f32_e32 v4, 0x4f7ffffe, v4
	v_cvt_u32_f32_e32 v4, v4
	v_mul_lo_u32 v1, v3, v4
	v_mul_hi_u32 v1, v4, v1
	v_add_u32_e32 v1, v4, v1
	v_mul_hi_u32 v1, v5, v1
	v_mul_lo_u32 v3, v1, v2
	v_sub_u32_e32 v3, v5, v3
	v_add_u32_e32 v4, 1, v1
	v_cmp_ge_u32_e32 vcc, v3, v2
	s_nop 1
	v_cndmask_b32_e32 v1, v1, v4, vcc
	v_sub_u32_e32 v4, v3, v2
	v_cndmask_b32_e32 v3, v3, v4, vcc
	v_add_u32_e32 v4, 1, v1
	v_cmp_ge_u32_e32 vcc, v3, v2
	v_add_u32_e32 v3, 1, v5
	s_nop 0
	v_cndmask_b32_e32 v1, v1, v4, vcc
	v_mul_lo_u32 v4, v2, v1
	v_add_u32_e32 v2, v4, v2
	v_cmp_ne_u32_e32 vcc, v3, v2
	s_and_saveexec_b64 s[0:1], vcc
	s_xor_b64 s[8:9], exec, s[0:1]
	s_cbranch_execz .LBB0_714
	s_waitcnt lgkmcnt(0)
	s_cmp_lg_u32 s98, 0
	s_cbranch_scc1 .Llp3_std
	v_mov_b32_e32 v0, 0x1000
	s_mov_b32 s14, 0
.Llp3_spin:
	global_load_dword v4, v0, s[6:7] offset:1024 sc1
	s_waitcnt vmcnt(0)
	v_cmp_lt_u32_e32 vcc, v4, v2
	s_cbranch_vccz .Llp3_out
	s_sleep 1
	s_add_i32 s14, s14, 1
	s_cmp_lt_u32 s14, 0x100000
	s_cbranch_scc1 .Llp3_spin
.Llp3_out:
	s_mov_b64 s[10:11], exec
	s_branch .LBB0_713
.Llp3_std:
	v_mov_b32_e32 v0, 0x2000
	global_load_dword v0, v0, s[6:7] offset:1024 sc1
	s_add_u32 s14, s6, 0x2400
	s_addc_u32 s15, s7, 0
	s_waitcnt vmcnt(0)
	v_cmp_eq_u32_e32 vcc, v0, v1
	s_and_saveexec_b64 s[10:11], vcc
	s_cbranch_execz .LBB0_713
	s_add_u32 s12, s50, 0x1180200
	s_addc_u32 s13, s51, 0
	s_mov_b32 s0, 1
	s_mov_b64 s[16:17], 0
	v_mov_b32_e32 v0, 0
	s_branch .LBB0_704

; __device__ __forceinline__ unsigned xb_add(unsigned* p, unsigned v) { return __hip_atomic_fetch_add(p, v, __ATOMIC_RELAXED, __HIP_MEMORY_SCOPE_AGENT); }
; __device__ __forceinline__ void xcd_barrier(const XcdBarrier& b) {
;     ...
;             __builtin_amdgcn_fence(__ATOMIC_ACQUIRE, "agent");
;             xb_add(&bar[XB_XGEN(b.x)], 1u);
;             asm volatile("s_waitcnt vmcnt(0)" ::: "memory");
.LBB0_731:
	s_or_b64 exec, exec, s[10:11]
	s_mov_b64 s[10:11], exec
	v_mbcnt_lo_u32_b32 v0, s10, 0
	v_mbcnt_hi_u32_b32 v0, s11, v0
	v_cmp_eq_u32_e32 vcc, 0, v0
	s_waitcnt vmcnt(0)
	buffer_inv sc1
	s_cmp_eq_u32 s98, 0
	s_cbranch_scc1 .Lnx3
	s_and_saveexec_b64 s[12:13], vcc
	s_cbranch_execz .LBB0_733
	s_bcnt1_i32_b64 s0, s[10:11]
	v_mov_b32_e32 v0, 0x2000
	v_mov_b32_e32 v1, s0
	global_atomic_add v0, v1, s[6:7] offset:1024
.LBB0_733:
	s_or_b64 exec, exec, s[12:13]
.Lnx3:
	s_waitcnt vmcnt(0)
.LBB0_734:
	s_or_b64 exec, exec, s[8:9]

; __device__ __forceinline__ unsigned xb_ld(unsigned* p)              { return __hip_atomic_load(p, __ATOMIC_RELAXED, __HIP_MEMORY_SCOPE_AGENT); }
; __device__ __forceinline__ unsigned xb_add(unsigned* p, unsigned v) { return __hip_atomic_fetch_add(p, v, __ATOMIC_RELAXED, __HIP_MEMORY_SCOPE_AGENT); }
; #define XB_SPIN(cond, bar) do { unsigned _sp = 0; while (cond) { __builtin_amdgcn_s_sleep(1); \
;     if ((++_sp & 255u) == 0u) { if (xb_ld(&(bar)[XB_TMO])) break; if (_sp > XB_SPIN_CAP) { atomicAdd(&(bar)[XB_TMO], 1u); break; } } } } while (0)
; __device__ __forceinline__ void xcd_barrier(const XcdBarrier& b) {
;     ...
;         const unsigned old = xb_add(&bar[XB_XSUB(b.x)], 1u);
;         const unsigned gen = old / nloc;
;         if (old + 1u == (gen + 1u) * nloc) {
;             __builtin_amdgcn_fence(__ATOMIC_RELEASE, "agent");
;             asm volatile("s_waitcnt vmcnt(0)" ::: "memory");
;             const unsigned og = xb_add(&bar[XB_TOP], 1u);
;             const unsigned tg = og / nx;
;             if (og + 1u == (tg + 1u) * nx) xb_add(&bar[XB_TOPGEN], 1u);
;             else XB_SPIN(xb_ld(&bar[XB_TOPGEN]) == tg, bar);
;             __builtin_amdgcn_fence(__ATOMIC_ACQUIRE, "agent");
;             xb_add(&bar[XB_XGEN(b.x)], 1u);
;             asm volatile("s_waitcnt vmcnt(0)" ::: "memory");
;         } else {
;             XB_SPIN(xb_ld(&bar[XB_XGEN(b.x)]) == gen, bar);
.LBB0_791:
	s_or_b64 exec, exec, s[10:11]
	v_cvt_f32_u32_e32 v4, v2
	s_waitcnt vmcnt(0)
	v_readfirstlane_b32 s2, v3
	v_sub_u32_e32 v3, 0, v2
	v_rcp_iflag_f32_e32 v4, v4
	v_add_u32_e32 v5, s2, v1
	v_mul_f32_e32 v4, 0x4f7ffffe, v4
	v_cvt_u32_f32_e32 v4, v4
	v_mul_lo_u32 v1, v3, v4
	v_mul_hi_u32 v1, v4, v1
	v_add_u32_e32 v1, v4, v1
	v_mul_hi_u32 v1, v5, v1
	v_mul_lo_u32 v3, v1, v2
	v_sub_u32_e32 v3, v5, v3
	v_add_u32_e32 v4, 1, v1
	v_cmp_ge_u32_e32 vcc, v3, v2
	s_nop 1
	v_cndmask_b32_e32 v1, v1, v4, vcc
	v_sub_u32_e32 v4, v3, v2
	v_cndmask_b32_e32 v3, v3, v4, vcc
	v_add_u32_e32 v4, 1, v1
	v_cmp_ge_u32_e32 vcc, v3, v2
	v_add_u32_e32 v3, 1, v5
	s_nop 0
	v_cndmask_b32_e32 v1, v1, v4, vcc
	v_mul_lo_u32 v4, v2, v1
	v_add_u32_e32 v2, v4, v2
	v_cmp_ne_u32_e32 vcc, v3, v2
	s_and_saveexec_b64 s[8:9], vcc
	s_xor_b64 s[8:9], exec, s[8:9]
	s_cbranch_execz .LBB0_805
	s_waitcnt lgkmcnt(0)
	s_cmp_lg_u32 s98, 0
	s_cbranch_scc1 .Llp4_std
	v_mov_b32_e32 v0, 0x1000
	s_mov_b32 s14, 0

; __device__ __forceinline__ unsigned xb_ld(unsigned* p)              { return __hip_atomic_load(p, __ATOMIC_RELAXED, __HIP_MEMORY_SCOPE_AGENT); }
; #define XB_SPIN(cond, bar) do { unsigned _sp = 0; while (cond) { __builtin_amdgcn_s_sleep(1); \
;     if ((++_sp & 255u) == 0u) { if (xb_ld(&(bar)[XB_TMO])) break; if (_sp > XB_SPIN_CAP) { atomicAdd(&(bar)[XB_TMO], 1u); break; } } } } while (0)
; __device__ __forceinline__ void xcd_barrier(const XcdBarrier& b) {
;     ...
;             XB_SPIN(xb_ld(&bar[XB_XGEN(b.x)]) == gen, bar);
.Llp4_std:
	v_mov_b32_e32 v0, 0x2000
	global_load_dword v0, v0, s[4:5] offset:1024 sc1
	s_add_u32 s14, s4, 0x2400
	s_addc_u32 s15, s5, 0
	s_waitcnt vmcnt(0)
	v_cmp_eq_u32_e32 vcc, v0, v1
	s_and_saveexec_b64 s[10:11], vcc
	s_cbranch_execz .LBB0_804
	s_add_u32 s12, s50, 0x1180200
	s_addc_u32 s13, s51, 0
	s_mov_b32 s2, 1
	s_mov_b64 s[16:17], 0
	v_mov_b32_e32 v0, 0
	s_branch .LBB0_795

; __device__ __forceinline__ unsigned xb_add(unsigned* p, unsigned v) { return __hip_atomic_fetch_add(p, v, __ATOMIC_RELAXED, __HIP_MEMORY_SCOPE_AGENT); }
; __device__ __forceinline__ void xcd_barrier(const XcdBarrier& b) {
;     ...
;             __builtin_amdgcn_fence(__ATOMIC_ACQUIRE, "agent");
;             xb_add(&bar[XB_XGEN(b.x)], 1u);
;             asm volatile("s_waitcnt vmcnt(0)" ::: "memory");
.LBB0_822:
	s_or_b64 exec, exec, s[10:11]
	s_mov_b64 s[10:11], exec
	v_mbcnt_lo_u32_b32 v0, s10, 0
	v_mbcnt_hi_u32_b32 v0, s11, v0
	v_cmp_eq_u32_e32 vcc, 0, v0
	s_waitcnt vmcnt(0)
	buffer_inv sc1
	s_cmp_eq_u32 s98, 0
	s_cbranch_scc1 .Lnx4
	s_and_saveexec_b64 s[12:13], vcc
	s_cbranch_execz .LBB0_824
	s_bcnt1_i32_b64 s2, s[10:11]
	v_mov_b32_e32 v0, 0x2000
	v_mov_b32_e32 v1, s2
	global_atomic_add v0, v1, s[4:5] offset:1024
.LBB0_824:
	s_or_b64 exec, exec, s[12:13]
.Lnx4:
	s_waitcnt vmcnt(0)
.LBB0_825:
	s_or_b64 exec, exec, s[8:9]

; __device__ __forceinline__ unsigned xb_ld(unsigned* p)              { return __hip_atomic_load(p, __ATOMIC_RELAXED, __HIP_MEMORY_SCOPE_AGENT); }
; #define XB_SPIN(cond, bar) do { unsigned _sp = 0; while (cond) { __builtin_amdgcn_s_sleep(1); \
;     if ((++_sp & 255u) == 0u) { if (xb_ld(&(bar)[XB_TMO])) break; if (_sp > XB_SPIN_CAP) { atomicAdd(&(bar)[XB_TMO], 1u); break; } } } } while (0)
; __device__ __forceinline__ void xcd_barrier(const XcdBarrier& b) {
;     ...
;             XB_SPIN(xb_ld(&bar[XB_XGEN(b.x)]) == gen, bar);
.Llp5_std:
	v_mov_b32_e32 v0, 0x2000
	global_load_dword v0, v0, s[4:5] offset:1024 sc1
	s_add_u32 s14, s4, 0x2400
	s_addc_u32 s15, s5, 0
	s_waitcnt vmcnt(0)
	v_cmp_eq_u32_e32 vcc, v0, v1
	s_and_saveexec_b64 s[8:9], vcc
	s_cbranch_execz .LBB0_886
	s_add_u32 s12, s50, 0x1180200
	s_addc_u32 s13, s51, 0
	s_mov_b32 s2, 1
	s_mov_b64 s[16:17], 0
	v_mov_b32_e32 v0, 0
	s_branch .LBB0_877

; __device__ __forceinline__ unsigned xb_add(unsigned* p, unsigned v) { return __hip_atomic_fetch_add(p, v, __ATOMIC_RELAXED, __HIP_MEMORY_SCOPE_AGENT); }
; __device__ __forceinline__ void xcd_barrier(const XcdBarrier& b) {
;     ...
;             __builtin_amdgcn_fence(__ATOMIC_ACQUIRE, "agent");
;             xb_add(&bar[XB_XGEN(b.x)], 1u);
;             asm volatile("s_waitcnt vmcnt(0)" ::: "memory");
.LBB0_904:
	s_or_b64 exec, exec, s[8:9]
	s_mov_b64 s[8:9], exec
	v_mbcnt_lo_u32_b32 v0, s8, 0
	v_mbcnt_hi_u32_b32 v0, s9, v0
	v_cmp_eq_u32_e32 vcc, 0, v0
	s_waitcnt vmcnt(0)
	buffer_inv sc1
	s_cmp_eq_u32 s98, 0
	s_cbranch_scc1 .Lnx5
	s_and_saveexec_b64 s[12:13], vcc
	s_cbranch_execz .LBB0_906
	s_bcnt1_i32_b64 s2, s[8:9]
	v_mov_b32_e32 v0, 0x2000
	v_mov_b32_e32 v1, s2
	global_atomic_add v0, v1, s[4:5] offset:1024
.LBB0_906:
	s_or_b64 exec, exec, s[12:13]
.Lnx5:
	s_waitcnt vmcnt(0)
.LBB0_907:
	s_or_b64 exec, exec, s[6:7]

; template <class Epi, class Sched, bool ALIGN_EPI = false, bool SP2 = false>
; __device__ __forceinline__ void gemm_phase(PG8_LAS unsigned char* lds, const Gemm g, const Sched& S, const Epi& E) {
;     ...
;     for (int i = 0; i < 2; ++i) { int R, C; stage_rc(tid * 16 + i * 8192, R, C); const int Rb = Epi::PERM ? ((R & ~31) + perm32(R & 31)) : R;
;         voffA[i] = (unsigned)(R * K + C) * 2u; voffB[i] = (unsigned)(Rb * K + C) * 2u; }
;     const size_t kstep = (size_t)(BK * 2);
;     const size_t hstep = (size_t)HALF * K * 2;
;     const size_t tstep = 2 * hstep;
;     const unsigned ldsw = (unsigned)wid * 1024u;
;     const int aoff = lds_byte(wr * 64 + fr, fq * 8), boff = lds_byte(wc * 32 + fr, fq * 8);
;     ...
;     Unit cur, nxt; int ui = 0;
;     if (!S.next(0, cur)) return;
;     f32x4 acc[2][2][4][2];
; #pragma unroll
;     for (int a = 0; a < 2; ++a)
; #pragma unroll
;         for (int b = 0; b < 2; ++b)
; #pragma unroll
;             for (int m = 0; m < 4; ++m)
; #pragma unroll
;                 for (int n = 0; n < 2; ++n) acc[a][b][m][n] = (f32x4){0.f, 0.f, 0.f, 0.f};
;     bf16x8 At[4][2], B0[2][2], B1[2][2];
;     const char* cA = (const char*)g.A + (size_t)cur.pm * tstep; const char* cB = (const char*)g.Bt + (size_t)cur.pn * tstep;
;     S.a_ready(cur);
;     if constexpr (SP2) {
;         PG8_STAGE(PG8_SB(0, 0), cB, voffB); PG8_STAGE(PG8_SB(0, 1), cB + hstep, voffB); PG8_STAGE(PG8_SA(0, 0), cA, voffA); PG8_STAGE(PG8_SA(0, 1), cA + hstep, voffA);
;         if (wr == 1) PG8_BAR;
;         PG8_WAIT_V(2); PG8_BAR;
;         PG8_STAGE(PG8_SB(1, 0), cB + kstep, voffB); PG8_STAGE(PG8_SA(1, 0), cA + kstep, voffA); PG8_STAGE(PG8_SB(1, 1), cB + hstep + kstep, voffB);
;         PG8_WAIT_V(6); PG8_BAR;
;     } else {
;         PG8_STAGE(PG8_SB(0, 0), cB, voffB); PG8_STAGE(PG8_SA(0, 0), cA, voffA); PG8_STAGE(PG8_SB(0, 1), cB + hstep, voffB); PG8_STAGE(PG8_SA(0, 1), cA + hstep, voffA);
;         if (wr == 1) PG8_BAR;
; __device__ __forceinline__ void xcd_barrier(const XcdBarrier& b) {
;     ...
;             xb_add(&bar[XB_XGEN(b.x)], 1u);
;             asm volatile("s_waitcnt vmcnt(0)" ::: "memory");
;         } else {
;             XB_SPIN(xb_ld(&bar[XB_XGEN(b.x)]) == gen, bar);
;             __builtin_amdgcn_fence(__ATOMIC_ACQUIRE, "agent");
;             asm volatile("s_waitcnt vmcnt(0)" ::: "memory");
;         }
;     }
;     __syncthreads();
.LBB0_977:
	s_or_b64 exec, exec, s[6:7]
	s_mov_b64 s[6:7], exec
	v_mbcnt_lo_u32_b32 v0, s6, 0
	v_mbcnt_hi_u32_b32 v0, s7, v0
	v_cmp_eq_u32_e32 vcc, 0, v0
	s_waitcnt vmcnt(0)
	buffer_inv sc1
	s_cmp_eq_u32 s98, 0
	s_cbranch_scc1 .Lnx6
	s_and_saveexec_b64 s[8:9], vcc
	s_cbranch_execz .LBB0_979
	s_bcnt1_i32_b64 s2, s[6:7]
	v_mov_b32_e32 v0, 0x2000
	v_mov_b32_e32 v1, s2
	global_atomic_add v0, v1, s[4:5] offset:1024
.LBB0_979:
	s_or_b64 exec, exec, s[8:9]
.Lnx6:
	s_waitcnt vmcnt(0)
.LBB0_980:
	s_or_b64 exec, exec, s[0:1]
	v_readlane_b32 s4, v255, 1
	v_readlane_b32 s5, v255, 2
	s_waitcnt lgkmcnt(0)
	s_barrier
	s_and_b64 vcc, exec, s[4:5]
	v_readfirstlane_b32 s1, v234
	s_cbranch_vccz .LBB0_1000
	v_lshlrev_b32_e32 v0, 4, v234
	v_add_u32_e32 v1, 0x2000, v0
	v_ashrrev_i32_e32 v2, 31, v1
	v_lshrrev_b32_e32 v2, 22, v2
	v_add_u32_e32 v2, v1, v2
	v_ashrrev_i32_e32 v8, 10, v2
	v_mul_i32_i24_e32 v2, 0x400, v8
	v_sub_u32_e32 v1, v1, v2
	v_lshrrev_b32_e32 v2, 4, v1
	v_bitop3_b32 v1, v2, v1, 32 bitop3:0x6c
	v_ashrrev_i32_e32 v2, 31, v1
	v_lshrrev_b32_e32 v2, 26, v2
	v_add_u32_e32 v2, v1, v2
	v_lshlrev_b32_e32 v3, 3, v8
	v_ashrrev_i32_e32 v9, 6, v2
	v_and_b32_e32 v3, -16, v3
	v_add_u32_e32 v3, v9, v3
	v_and_b32_e32 v4, 3, v9
	s_mov_b32 s0, 0x1fffe0
	v_lshrrev_b32_e32 v5, 2, v3
	v_lshlrev_b32_e32 v6, 1, v3
	v_and_b32_e32 v2, 0xc0, v2
	v_and_or_b32 v4, v3, s0, v4
	v_and_b32_e32 v5, 4, v5
	v_and_b32_e32 v6, 24, v6
	v_sub_u32_e32 v1, v1, v2
	v_mov_b32_e32 v2, 1
	v_or3_b32 v4, v4, v5, v6
	v_lshlrev_b32_e32 v5, 5, v8
	v_ashrrev_i16_sdwa v1, v2, sext(v1) dst_sel:DWORD dst_unused:UNUSED_PAD src0_sel:DWORD src1_sel:BYTE_0
	v_and_b32_e32 v5, 32, v5
	v_bfe_i32 v10, v1, 0, 16
	v_add_lshl_u32 v1, v5, v10, 1
	v_lshl_add_u32 v128, v4, 11, v1
	v_lshl_add_u32 v130, v3, 11, v1
	v_bfe_i32 v1, v234, 27, 1
	v_lshrrev_b32_e32 v1, 22, v1
	v_add_u32_e32 v1, v0, v1
	v_and_b32_e32 v1, 0xfffffc00, v1
	v_sub_u32_e32 v0, v0, v1
	v_lshrrev_b32_e32 v1, 4, v0
	v_ashrrev_i32_e32 v3, 31, v234
	v_bitop3_b32 v0, v1, v0, 32 bitop3:0x6c
	v_lshrrev_b32_e32 v3, 26, v3
	v_ashrrev_i32_e32 v1, 31, v0
	v_add_u32_e32 v3, v234, v3
	v_lshrrev_b32_e32 v1, 26, v1
	v_ashrrev_i32_e32 v12, 6, v3
	v_add_u32_e32 v1, v0, v1
	v_lshlrev_b32_e32 v3, 3, v12
	v_ashrrev_i32_e32 v11, 6, v1
	v_and_b32_e32 v3, -16, v3
	v_add_u32_e32 v3, v11, v3
	v_and_b32_e32 v4, 3, v11
	v_and_or_b32 v4, v3, s0, v4
	s_lshr_b32 s0, s93, 29
	s_add_i32 s0, s3, s0
	s_ashr_i32 s4, s0, 3
	s_and_b32 s0, s0, -8
	s_ashr_i32 s6, s1, 6
	s_sub_i32 s0, s3, s0
	s_ashr_i32 s8, s1, 8
	s_lshl_b32 s2, s6, 10
	s_lshl_b32 s7, s0, 6
	s_mul_i32 s5, s0, 0x41
	s_cmp_lt_i32 s0, 0
	s_cselect_b32 s0, s5, s7
	s_add_i32 s0, s0, s4
	s_ashr_i32 s4, s0, 31
	s_lshr_b32 s4, s4, 27
	s_add_i32 s4, s0, s4
	s_ashr_i32 s5, s4, 5
	s_and_b32 s4, s4, 0xffe0
	s_sub_i32 s4, s0, s4
	s_bfe_i32 s0, s4, 0x80000
	s_bfe_u32 s0, s0, 0x3000c
	s_add_i32 s7, s4, s0
	s_bfe_i32 s0, s7, 0x80000
	s_and_b32 s7, s7, 0xf8
	s_sub_i32 s4, s4, s7
	s_lshl_b32 s5, s5, 3
	s_sext_i32_i16 s0, s0
	s_sext_i32_i8 s4, s4
	v_lshrrev_b32_e32 v5, 2, v3
	v_lshlrev_b32_e32 v6, 1, v3
	v_and_b32_e32 v1, 0xc0, v1
	s_lshr_b32 s0, s0, 3
	s_add_i32 s34, s5, s4
	v_and_b32_e32 v5, 4, v5
	v_and_b32_e32 v6, 24, v6
	v_sub_u32_e32 v0, v0, v1
	s_ashr_i32 s35, s34, 31
	s_bfe_i64 s[10:11], s[0:1], 0x100000
	v_or3_b32 v4, v4, v5, v6
	v_lshlrev_b32_e32 v5, 5, v12
	v_ashrrev_i16_sdwa v0, v2, sext(v0) dst_sel:DWORD dst_unused:UNUSED_PAD src0_sel:DWORD src1_sel:BYTE_0
	s_lshl_b64 s[4:5], s[34:35], 19
	s_lshl_b64 s[10:11], s[10:11], 19
	v_and_b32_e32 v5, 32, v5
	v_bfe_i32 v13, v0, 0, 16
	s_add_u32 s38, s28, s10
	v_add_lshl_u32 v0, v5, v13, 1
	s_addc_u32 s39, s29, s11
	s_add_i32 s25, s2, 0
	v_lshl_add_u32 v132, v4, 11, v0
	s_add_i32 m0, s25, 0x10000
	v_lshl_add_u32 v134, v3, 11, v0
	global_load_lds_dwordx4 v132, s[38:39]
	s_add_i32 m0, s25, 0x12000
	s_add_u32 s10, s38, 0x40000
	global_load_lds_dwordx4 v128, s[38:39]
	s_addc_u32 s11, s39, 0
	s_add_i32 m0, s25, 0x14000
	v_mov_b32_e32 v133, 0
	global_load_lds_dwordx4 v132, s[10:11]
	s_add_i32 m0, s25, 0x16000
	s_add_u32 s36, s26, s4
	s_addc_u32 s37, s27, s5
	s_add_i32 s33, s25, 0x2000
	global_load_lds_dwordx4 v128, s[10:11]
	s_mov_b32 m0, s25
	s_add_u32 s4, s36, 0x40000
	global_load_lds_dwordx4 v134, s[36:37]
	s_mov_b32 m0, s33
	s_addc_u32 s5, s37, 0
	s_add_i32 s35, s25, 0x4000
	global_load_lds_dwordx4 v130, s[36:37]
	s_mov_b32 m0, s35
	s_add_i32 s42, s25, 0x6000
	global_load_lds_dwordx4 v134, s[4:5]
	s_mov_b32 m0, s42
	v_mov_b32_e32 v129, v133
	global_load_lds_dwordx4 v130, s[4:5]
	v_mov_b32_e32 v135, v133
	v_mov_b32_e32 v131, v133
	s_cmp_eq_u32 s8, 1
	s_mov_b32 s43, 0
	v_lshl_add_u64 v[6:7], s[38:39], 0, v[132:133]
	v_lshl_add_u64 v[4:5], s[38:39], 0, v[128:129]
	v_lshl_add_u64 v[0:1], s[36:37], 0, v[134:135]
	s_cselect_b64 s[4:5], -1, 0
	s_cmp_lg_u32 s8, 1
	v_lshl_add_u64 v[2:3], s[36:37], 0, v[130:131]
	s_cbranch_scc1 .LBB0_983
	s_barrier
